# attention: static s_setprio 3 (instead of 1) for waves 4-7
# speedup vs baseline: 1.0007x; 1.0007x over previous
; #define QF(d, e) __uint_as_float(((unsigned)(unsigned short)qr[d][e]) << 16)
; template <typename TQ> ...
;     ...
;   const int tid = tid_, wid = __builtin_amdgcn_readfirstlane(tid >> 6), lane = tid & 63, r32 = lane & 31, hi = lane >> 5;
;   bf16* V_lds = (bf16*)lds; bf16* K_lds = (bf16*)(lds + 2 * SHM_V);
;   float* ws = (float*)(lds + 2 * SHM_V + 2 * SHM_K) + wid * 64; float* li_l = ws;
;   float l_reg = 0; f32x16 o[4] = {}; bf16x8 qr[8];
;   const TQ* Qw = Qb + (long)(wid * QBLK + r32) * LDQ + hi * 8;
; #pragma unroll
;   for (int d0 = 0; d0 < 8; ++d0) qr[d0] = SQ::tobf(SQ::ld8(Qw + d0 * 16));
;   const int sr = tid >> 4, sc = (tid & 15) * 8, vst0 = v_st(sr, sc), vst1 = v_st(32 + sr, sc);
;   const int vb0 = (int)(uintptr_t)V_lds + v_rd_base(lane);
;   struct { typename St::T vs0, vs1, ks0, ks1; } sr_[SDEPTH];
;     ...
;   constexpr int SE = 0, SO = SDEPTH - 1;
;   SLOAD(SE, 0);
;   {
;     float ss = 0.f;
;     ...
; #pragma unroll
;     for (int d0 = 0; d0 < 8; ++d0)
; #pragma unroll
;       for (int e = 0; e < 8; ++e) { const float x = QF(d0, e); ss += x * x; }
;     ss += __shfl_xor(ss, 32);
;     const float rn = (SCALE * 1.4426950408889634f) / sqrtf(ss * (1.0f / 128.0f) + 1e-6f);
;     const int t = trow0 + wid * QBLK + r32; const int prow = t >> 6, pcol = t & 63;
; #pragma unroll
;     for (int hf = 0; hf < 2; ++hf)
; #pragma unroll
;       for (int dd = 0; dd < 2; ++dd) {
;         const int dl = 4 * hf + dd, du = dl + 2;
;         const int f0 = 16 * dd + 8 * hi;
;         const float* cp = rc + (hf ? pcol : prow) * 32 + f0; const float* sp = rsn + (hf ? pcol : prow) * 32 + f0;
;         const float* gl = gq + 16 * dl + 8 * hi; const float* gu = gq + 16 * du + 8 * hi;
; __global__ void __launch_bounds__(NTHR, 2) fwd_megakernel(KArgs a) {
;     ...
;         for (int i = 0; i < upb; ++i) {
;             const int unit = vcu * upb + i; if (unit >= 512) break;
;             const int grp = unit >> 7, rem = unit & 127, gq = rem >> 5, qb = rem & 31, b = grp >> 1, kvh = grp & 1, h = kvh * 4 + gq;
;             const size_t qoff = ((size_t)(b * SEQ + qb * 256)) * DM + h * 128, koff = (size_t)b * SKV * 256 + kvh * 128;
;             att::attn_dense_body<att::bf16>(Q + qoff, Kb + koff, Vb + koff, O + qoff, SKV, (char*)lds_raw, mC, a.g_q, (const float*)(ws + WS_ROPE), (const float*)(ws + WS_ROPE) + 4096, qb * 256);
.LBB0_819:
	s_add_i32 s12, s74, s73
	s_cmpk_gt_i32 s12, 0x1ff
	s_mov_b64 s[0:1], -1
	s_cbranch_scc1 .LBB0_818
	s_lshl_b32 s0, s94, 1
	s_ashr_i32 s96, s12, 8
	s_lshl_b32 s1, s12, 8
	s_and_b32 s95, s0, 0x100
	s_lshl_b32 s0, s96, 13
	s_and_b32 s33, s1, 0x1f00
	s_bfe_u32 s15, s12, 0x10007
	s_or_b32 s0, s0, s33
	s_lshl_b32 s12, s12, 2
	s_ashr_i32 s1, s0, 31
	s_lshl_b32 s13, s15, 9
	s_and_b32 s12, s12, 0x180
	s_lshl_b64 s[0:1], s[0:1], 10
	s_or_b32 s12, s13, s12
	s_or_b32 s0, s0, s12
	s_mul_i32 s12, s96, 0x210000
	s_lshl_b32 s15, s15, 7
	s_or_b32 s12, s12, s15
	s_lshl_b64 s[48:49], s[0:1], 1
	s_mul_hi_i32 s13, s96, 0x210000
	s_add_u32 s0, s20, s48
	s_addc_u32 s1, s21, s49
	s_lshl_b64 s[12:13], s[12:13], 1
	s_add_u32 s54, s69, s12
	s_addc_u32 s55, s70, s13
	v_mov_b32_e32 v114, v0
	s_add_u32 s64, s67, s12
	s_addc_u32 s65, s68, s13
	v_readfirstlane_b32 s53, v114
	s_lshr_b32 s15, s53, 6
	s_lshl_b32 s80, s15, 11
	s_add_u32 s79, s80, 0x10000
	s_lshl_b32 s52, s15, 5
	s_lshl_b32 s12, s15, 3
	v_and_b32_e32 v1, 63, v0
	v_and_b32_e32 v16, 15, v1
	v_lshrrev_b32_e32 v17, 4, v1
	v_add_u32_e32 v12, s12, v17
	v_and_b32_e32 v6, 15, v12
	v_xor_b32_e32 v6, v6, v16
	v_lshlrev_b32_e32 v6, 4, v6
	v_lshl_or_b32 v246, v12, 9, v6
	v_and_b32_e32 v6, 7, v12
	v_lshrrev_b32_e32 v7, 1, v16
	v_xor_b32_e32 v6, v6, v7
	v_and_b32_e32 v7, 1, v16
	v_lshl_or_b32 v6, v6, 1, v7
	v_lshlrev_b32_e32 v6, 4, v6
	v_lshl_or_b32 v248, v12, 9, v6
	v_add_u32_e32 v12, s12, v17
	v_add_u32_e32 v12, 4, v12
	v_and_b32_e32 v6, 15, v12
	v_xor_b32_e32 v6, v6, v16
	v_lshlrev_b32_e32 v6, 4, v6
	v_lshl_or_b32 v247, v12, 9, v6
	v_and_b32_e32 v6, 7, v12
	v_lshrrev_b32_e32 v7, 1, v16
	v_xor_b32_e32 v6, v6, v7
	v_and_b32_e32 v7, 1, v16
	v_lshl_or_b32 v6, v6, 1, v7
	v_lshlrev_b32_e32 v6, 4, v6
	v_lshl_or_b32 v249, v12, 9, v6
	s_mov_b32 s98, s54
	s_mov_b32 s99, s55
	s_mov_b32 s100, s64
	s_mov_b32 s101, s65
	s_add_u32 m0, s79, 0
	s_nop 0
	global_load_lds_dwordx4 v246, s[98:99]
	s_add_u32 m0, s79, 1024
	s_nop 0
	global_load_lds_dwordx4 v247, s[98:99]
	s_add_u32 m0, s80, 0
	s_nop 0
	global_load_lds_dwordx4 v248, s[100:101]
	s_add_u32 m0, s80, 1024
	s_nop 0
	global_load_lds_dwordx4 v249, s[100:101]
	s_add_u32 s98, s98, 0x8000
	s_addc_u32 s99, s99, 0
	s_add_u32 s100, s100, 0x8000
	s_addc_u32 s101, s101, 0
	s_add_u32 m0, s79, 16384
	s_nop 0
	global_load_lds_dwordx4 v246, s[98:99]
	s_add_u32 m0, s79, 17408
	s_nop 0
	global_load_lds_dwordx4 v247, s[98:99]
	s_add_u32 m0, s80, 16384
	s_nop 0
	global_load_lds_dwordx4 v248, s[100:101]
	s_add_u32 m0, s80, 17408
	s_nop 0
	global_load_lds_dwordx4 v249, s[100:101]
	s_add_u32 s98, s98, 0x8000
	s_addc_u32 s99, s99, 0
	s_add_u32 s100, s100, 0x8000
	s_addc_u32 s101, s101, 0
	s_add_u32 m0, s79, 32768
	s_nop 0
	global_load_lds_dwordx4 v246, s[98:99]
	s_add_u32 m0, s79, 33792
	s_nop 0
	global_load_lds_dwordx4 v247, s[98:99]
	s_add_u32 m0, s80, 32768
	s_nop 0
	global_load_lds_dwordx4 v248, s[100:101]
	s_add_u32 m0, s80, 33792
	s_nop 0
	global_load_lds_dwordx4 v249, s[100:101]
	s_add_u32 s98, s98, 0x8000
	s_addc_u32 s99, s99, 0
	s_add_u32 m0, s79, 49152
	s_nop 0
	global_load_lds_dwordx4 v246, s[98:99]
	s_add_u32 m0, s79, 50176
	s_nop 0
	global_load_lds_dwordx4 v247, s[98:99]
	v_add_u32_e32 v6, s52, v16
	v_lshlrev_b32_e32 v6, 11, v6
	v_lshl_or_b32 v13, v17, 4, v6
	v_add_u32_e32 v14, 0x8000, v13
	global_load_dwordx4 v[146:149], v13, s[0:1] offset:0
	global_load_dwordx4 v[150:153], v13, s[0:1] offset:64
	global_load_dwordx4 v[154:157], v13, s[0:1] offset:128
	global_load_dwordx4 v[158:161], v13, s[0:1] offset:192
	global_load_dwordx4 v[162:165], v14, s[0:1] offset:0
	global_load_dwordx4 v[166:169], v14, s[0:1] offset:64
	global_load_dwordx4 v[170:173], v14, s[0:1] offset:128
	global_load_dwordx4 v[174:177], v14, s[0:1] offset:192
	v_lshlrev_b32_e32 v15, 5, v17
	global_load_dwordx4 v[18:21], v15, s[26:27] offset:0
	global_load_dwordx4 v[22:25], v15, s[26:27] offset:16
	global_load_dwordx4 v[26:29], v15, s[26:27] offset:128
	global_load_dwordx4 v[30:33], v15, s[26:27] offset:144
	global_load_dwordx4 v[34:37], v15, s[26:27] offset:256
	global_load_dwordx4 v[38:41], v15, s[26:27] offset:272
	global_load_dwordx4 v[42:45], v15, s[26:27] offset:384
	global_load_dwordx4 v[46:49], v15, s[26:27] offset:400
	s_add_u32 s13, s33, s52
	s_lshr_b32 s13, s13, 6
	s_lshl_b32 s13, s13, 7
	v_add_u32_e32 v200, s13, v15
	global_load_dwordx4 v[82:85], v200, s[4:5] offset:0
	global_load_dwordx4 v[90:93], v200, s[6:7] offset:0
	global_load_dwordx4 v[86:89], v200, s[4:5] offset:16
	global_load_dwordx4 v[94:97], v200, s[6:7] offset:16
	v_add_u32_e32 v6, s52, v16
	v_and_b32_e32 v6, 63, v6
	v_lshl_or_b32 v200, v6, 7, v15
	global_load_dwordx4 v[98:101], v200, s[4:5] offset:0
	global_load_dwordx4 v[106:109], v200, s[6:7] offset:0
	global_load_dwordx4 v[102:105], v200, s[4:5] offset:16
	global_load_dwordx4 v[110:113], v200, s[6:7] offset:16
	v_add_u32_e32 v6, s52, v16
	v_add_u32_e32 v6, 16, v6
	v_and_b32_e32 v6, 63, v6
	v_lshl_or_b32 v200, v6, 7, v15
	global_load_dwordx4 v[114:117], v200, s[4:5] offset:0
	global_load_dwordx4 v[122:125], v200, s[6:7] offset:0
	global_load_dwordx4 v[118:121], v200, s[4:5] offset:16
	global_load_dwordx4 v[126:129], v200, s[6:7] offset:16
	v_lshlrev_b32_e32 v7, 8, v16
	v_or_b32_e32 v6, 0, v17
	v_xor_b32_e32 v6, v6, v16
	v_lshl_or_b32 v6, v6, 4, v7
	v_add_u32_e32 v234, 0x10000, v6
	v_or_b32_e32 v6, 4, v17
	v_xor_b32_e32 v6, v6, v16
	v_lshl_or_b32 v6, v6, 4, v7
	v_add_u32_e32 v235, 0x10000, v6
	v_or_b32_e32 v6, 8, v17
	v_xor_b32_e32 v6, v6, v16
	v_lshl_or_b32 v6, v6, 4, v7
	v_add_u32_e32 v236, 0x10000, v6
	v_or_b32_e32 v6, 12, v17
	v_xor_b32_e32 v6, v6, v16
	v_lshl_or_b32 v6, v6, 4, v7
	v_add_u32_e32 v237, 0x10000, v6
	v_bfe_u32 v6, v1, 2, 2
	v_lshl_or_b32 v6, v17, 2, v6
	v_and_b32_e32 v201, 7, v6
	v_and_b32_e32 v7, 3, v1
	v_lshlrev_b32_e32 v7, 3, v7
	v_lshl_or_b32 v7, v6, 8, v7
	v_xor_b32_e32 v12, 0, v201
	v_lshl_or_b32 v238, v12, 5, v7
	v_xor_b32_e32 v12, 1, v201
	v_lshl_or_b32 v239, v12, 5, v7
	v_xor_b32_e32 v12, 2, v201
	v_lshl_or_b32 v240, v12, 5, v7
	v_xor_b32_e32 v12, 3, v201
	v_lshl_or_b32 v241, v12, 5, v7
	v_xor_b32_e32 v12, 4, v201
	v_lshl_or_b32 v242, v12, 5, v7
	v_xor_b32_e32 v12, 5, v201
	v_lshl_or_b32 v243, v12, 5, v7
	v_xor_b32_e32 v12, 6, v201
	v_lshl_or_b32 v244, v12, 5, v7
	v_xor_b32_e32 v12, 7, v201
	v_lshl_or_b32 v245, v12, 5, v7
	s_waitcnt vmcnt(0)
; #define QF(d, e) __uint_as_float(((unsigned)(unsigned short)qr[d][e]) << 16)
; template <typename TQ> ...
;     ...
;   {
;     float ss = 0.f;
;     ...
; #pragma unroll
;     for (int d0 = 0; d0 < 8; ++d0)
; #pragma unroll
;       for (int e = 0; e < 8; ++e) { const float x = QF(d0, e); ss += x * x; }
;     ss += __shfl_xor(ss, 32);
;     const float rn = (SCALE * 1.4426950408889634f) / sqrtf(ss * (1.0f / 128.0f) + 1e-6f);
;     const int t = trow0 + wid * QBLK + r32; const int prow = t >> 6, pcol = t & 63;
; #pragma unroll
;     for (int hf = 0; hf < 2; ++hf)
; #pragma unroll
;       for (int dd = 0; dd < 2; ++dd) {
;         const int dl = 4 * hf + dd, du = dl + 2;
;         const int f0 = 16 * dd + 8 * hi;
;         const float* cp = rc + (hf ? pcol : prow) * 32 + f0; const float* sp = rsn + (hf ? pcol : prow) * 32 + f0;
;         const float* gl = gq + 16 * dl + 8 * hi; const float* gu = gq + 16 * du + 8 * hi;
;         unsigned wl[4], wu[4];
; #pragma unroll
;         for (int e = 0; e < 8; e += 2) {
;           float o1[2], o2[2];
; #pragma unroll
;           for (int k = 0; k < 2; ++k) { const float x1 = QF(dl, e + k) * rn * gl[e + k], x2 = QF(du, e + k) * rn * gu[e + k]; const float c = cp[e + k], sn = sp[e + k];
;             o1[k] = x1 * c - x2 * sn; o2[k] = x2 * c + x1 * sn; }
;           wl[e >> 1] = cvtpk(o1[0], o1[1]); wu[e >> 1] = cvtpk(o2[0], o2[1]);
;         }
	v_lshlrev_b32_e32 v50, 16, v146
	v_and_b32_e32 v51, 0xffff0000, v146
	v_lshlrev_b32_e32 v52, 16, v147
	v_and_b32_e32 v53, 0xffff0000, v147
	v_lshlrev_b32_e32 v54, 16, v148
	v_and_b32_e32 v55, 0xffff0000, v148
	v_lshlrev_b32_e32 v56, 16, v149
	v_and_b32_e32 v57, 0xffff0000, v149
	v_lshlrev_b32_e32 v58, 16, v150
	v_and_b32_e32 v59, 0xffff0000, v150
	v_lshlrev_b32_e32 v60, 16, v151
	v_and_b32_e32 v61, 0xffff0000, v151
	v_lshlrev_b32_e32 v62, 16, v152
	v_and_b32_e32 v63, 0xffff0000, v152
	v_lshlrev_b32_e32 v64, 16, v153
	v_and_b32_e32 v65, 0xffff0000, v153
	v_lshlrev_b32_e32 v66, 16, v154
	v_and_b32_e32 v67, 0xffff0000, v154
	v_lshlrev_b32_e32 v68, 16, v155
	v_and_b32_e32 v69, 0xffff0000, v155
	v_lshlrev_b32_e32 v70, 16, v156
	v_and_b32_e32 v71, 0xffff0000, v156
	v_lshlrev_b32_e32 v72, 16, v157
	v_and_b32_e32 v73, 0xffff0000, v157
	v_lshlrev_b32_e32 v74, 16, v158
	v_and_b32_e32 v75, 0xffff0000, v158
	v_lshlrev_b32_e32 v76, 16, v159
	v_and_b32_e32 v77, 0xffff0000, v159
	v_lshlrev_b32_e32 v78, 16, v160
	v_and_b32_e32 v79, 0xffff0000, v160
	v_lshlrev_b32_e32 v80, 16, v161
	v_and_b32_e32 v81, 0xffff0000, v161
	v_mul_f32_e32 v130, v50, v50
	v_fmac_f32_e32 v130, v51, v51
	v_fmac_f32_e32 v130, v52, v52
	v_fmac_f32_e32 v130, v53, v53
	v_fmac_f32_e32 v130, v54, v54
	v_fmac_f32_e32 v130, v55, v55
	v_fmac_f32_e32 v130, v56, v56
	v_fmac_f32_e32 v130, v57, v57
	v_fmac_f32_e32 v130, v58, v58
	v_fmac_f32_e32 v130, v59, v59
	v_fmac_f32_e32 v130, v60, v60
	v_fmac_f32_e32 v130, v61, v61
	v_fmac_f32_e32 v130, v62, v62
	v_fmac_f32_e32 v130, v63, v63
	v_fmac_f32_e32 v130, v64, v64
	v_fmac_f32_e32 v130, v65, v65
	v_fmac_f32_e32 v130, v66, v66
	v_fmac_f32_e32 v130, v67, v67
	v_fmac_f32_e32 v130, v68, v68
	v_fmac_f32_e32 v130, v69, v69
	v_fmac_f32_e32 v130, v70, v70
	v_fmac_f32_e32 v130, v71, v71
	v_fmac_f32_e32 v130, v72, v72
	v_fmac_f32_e32 v130, v73, v73
	v_fmac_f32_e32 v130, v74, v74
	v_fmac_f32_e32 v130, v75, v75
	v_fmac_f32_e32 v130, v76, v76
	v_fmac_f32_e32 v130, v77, v77
	v_fmac_f32_e32 v130, v78, v78
	v_fmac_f32_e32 v130, v79, v79
	v_fmac_f32_e32 v130, v80, v80
	v_fmac_f32_e32 v130, v81, v81
	ds_swizzle_b32 v132, v130 offset:swizzle(SWAP,16)
	s_waitcnt lgkmcnt(0)
	v_add_f32_e32 v130, v130, v132
	v_mov_b32_e32 v132, v130
	s_nop 1
	v_permlane32_swap_b32_e32 v130, v132
	v_add_f32_e32 v130, v130, v132
	v_fmamk_f32 v130, v130, 0x3c000000, v199
	v_rsq_f32_e32 v130, v130
	s_nop 0
	v_mul_f32_e32 v131, s77, v130
	v_mul_f32_e32 v50, v50, v131
	v_mul_f32_e32 v50, v50, v18
	v_mul_f32_e32 v51, v51, v131
	v_mul_f32_e32 v51, v51, v19
	v_mul_f32_e32 v52, v52, v131
	v_mul_f32_e32 v52, v52, v20
	v_mul_f32_e32 v53, v53, v131
	v_mul_f32_e32 v53, v53, v21
	v_mul_f32_e32 v54, v54, v131
	v_mul_f32_e32 v54, v54, v22
	v_mul_f32_e32 v55, v55, v131
	v_mul_f32_e32 v55, v55, v23
	v_mul_f32_e32 v56, v56, v131
	v_mul_f32_e32 v56, v56, v24
	v_mul_f32_e32 v57, v57, v131
	v_mul_f32_e32 v57, v57, v25
	v_mul_f32_e32 v58, v58, v131
	v_mul_f32_e32 v58, v58, v26
	v_mul_f32_e32 v59, v59, v131
	v_mul_f32_e32 v59, v59, v27
	v_mul_f32_e32 v60, v60, v131
	v_mul_f32_e32 v60, v60, v28
	v_mul_f32_e32 v61, v61, v131
	v_mul_f32_e32 v61, v61, v29
	v_mul_f32_e32 v62, v62, v131
	v_mul_f32_e32 v62, v62, v30
	v_mul_f32_e32 v63, v63, v131
	v_mul_f32_e32 v63, v63, v31
	v_mul_f32_e32 v64, v64, v131
	v_mul_f32_e32 v64, v64, v32
	v_mul_f32_e32 v65, v65, v131
	v_mul_f32_e32 v65, v65, v33
	v_mul_f32_e32 v66, v66, v131
	v_mul_f32_e32 v66, v66, v34
	v_mul_f32_e32 v67, v67, v131
	v_mul_f32_e32 v67, v67, v35
	v_mul_f32_e32 v68, v68, v131
	v_mul_f32_e32 v68, v68, v36
	v_mul_f32_e32 v69, v69, v131
	v_mul_f32_e32 v69, v69, v37
	v_mul_f32_e32 v70, v70, v131
	v_mul_f32_e32 v70, v70, v38
	v_mul_f32_e32 v71, v71, v131
	v_mul_f32_e32 v71, v71, v39
	v_mul_f32_e32 v72, v72, v131
	v_mul_f32_e32 v72, v72, v40
	v_mul_f32_e32 v73, v73, v131
	v_mul_f32_e32 v73, v73, v41
	v_mul_f32_e32 v74, v74, v131
	v_mul_f32_e32 v74, v74, v42
	v_mul_f32_e32 v75, v75, v131
	v_mul_f32_e32 v75, v75, v43
	v_mul_f32_e32 v76, v76, v131
	v_mul_f32_e32 v76, v76, v44
	v_mul_f32_e32 v77, v77, v131
	v_mul_f32_e32 v77, v77, v45
	v_mul_f32_e32 v78, v78, v131
	v_mul_f32_e32 v78, v78, v46
	v_mul_f32_e32 v79, v79, v131
	v_mul_f32_e32 v79, v79, v47
	v_mul_f32_e32 v80, v80, v131
	v_mul_f32_e32 v80, v80, v48
	v_mul_f32_e32 v81, v81, v131
	v_mul_f32_e32 v81, v81, v49
	v_mul_f32_e32 v133, v58, v90
	v_mul_f32_e32 v134, v50, v90
	v_fma_f32 v50, v50, v82, -v133
	v_fma_f32 v58, v58, v82, v134
	v_mul_f32_e32 v133, v59, v91
	v_mul_f32_e32 v134, v51, v91
	v_fma_f32 v51, v51, v83, -v133
	v_fma_f32 v59, v59, v83, v134
	v_mul_f32_e32 v133, v60, v92
	v_mul_f32_e32 v134, v52, v92
	v_fma_f32 v52, v52, v84, -v133
	v_fma_f32 v60, v60, v84, v134
	v_mul_f32_e32 v133, v61, v93
	v_mul_f32_e32 v134, v53, v93
	v_fma_f32 v53, v53, v85, -v133
	v_fma_f32 v61, v61, v85, v134
	v_mul_f32_e32 v133, v62, v94
	v_mul_f32_e32 v134, v54, v94
	v_fma_f32 v54, v54, v86, -v133
	v_fma_f32 v62, v62, v86, v134
	v_mul_f32_e32 v133, v63, v95
	v_mul_f32_e32 v134, v55, v95
	v_fma_f32 v55, v55, v87, -v133
	v_fma_f32 v63, v63, v87, v134
	v_mul_f32_e32 v133, v64, v96
	v_mul_f32_e32 v134, v56, v96
	v_fma_f32 v56, v56, v88, -v133
	v_fma_f32 v64, v64, v88, v134
	v_mul_f32_e32 v133, v65, v97
	v_mul_f32_e32 v134, v57, v97
	v_fma_f32 v57, v57, v89, -v133
	v_fma_f32 v65, v65, v89, v134
	v_mul_f32_e32 v133, v74, v106
	v_mul_f32_e32 v134, v66, v106
	v_fma_f32 v66, v66, v98, -v133
	v_fma_f32 v74, v74, v98, v134
	v_mul_f32_e32 v133, v75, v107
	v_mul_f32_e32 v134, v67, v107
	v_fma_f32 v67, v67, v99, -v133
	v_fma_f32 v75, v75, v99, v134
	v_mul_f32_e32 v133, v76, v108
	v_mul_f32_e32 v134, v68, v108
	v_fma_f32 v68, v68, v100, -v133
; #define QF(d, e) __uint_as_float(((unsigned)(unsigned short)qr[d][e]) << 16)
; template <typename TQ> ...
;     ...
;   {
;     float ss = 0.f;
;     ...
; #pragma unroll
;     for (int d0 = 0; d0 < 8; ++d0)
; #pragma unroll
;       for (int e = 0; e < 8; ++e) { const float x = QF(d0, e); ss += x * x; }
;     ss += __shfl_xor(ss, 32);
;     const float rn = (SCALE * 1.4426950408889634f) / sqrtf(ss * (1.0f / 128.0f) + 1e-6f);
;     const int t = trow0 + wid * QBLK + r32; const int prow = t >> 6, pcol = t & 63;
; #pragma unroll
;     for (int hf = 0; hf < 2; ++hf)
; #pragma unroll
;       for (int dd = 0; dd < 2; ++dd) {
;         const int dl = 4 * hf + dd, du = dl + 2;
;         const int f0 = 16 * dd + 8 * hi;
;         const float* cp = rc + (hf ? pcol : prow) * 32 + f0; const float* sp = rsn + (hf ? pcol : prow) * 32 + f0;
;         const float* gl = gq + 16 * dl + 8 * hi; const float* gu = gq + 16 * du + 8 * hi;
;         unsigned wl[4], wu[4];
; #pragma unroll
;         for (int e = 0; e < 8; e += 2) {
;           float o1[2], o2[2];
; #pragma unroll
;           for (int k = 0; k < 2; ++k) { const float x1 = QF(dl, e + k) * rn * gl[e + k], x2 = QF(du, e + k) * rn * gu[e + k]; const float c = cp[e + k], sn = sp[e + k];
;             o1[k] = x1 * c - x2 * sn; o2[k] = x2 * c + x1 * sn; }
;           wl[e >> 1] = cvtpk(o1[0], o1[1]); wu[e >> 1] = cvtpk(o2[0], o2[1]);
;         }
;         u32x4 vl = {wl[0], wl[1], wl[2], wl[3]}, vu = {wu[0], wu[1], wu[2], wu[3]};
;         qr[dl] = *reinterpret_cast<bf16x8*>(&vl); qr[du] = *reinterpret_cast<bf16x8*>(&vu);
	v_fma_f32 v76, v76, v100, v134
	v_mul_f32_e32 v133, v77, v109
	v_mul_f32_e32 v134, v69, v109
	v_fma_f32 v69, v69, v101, -v133
	v_fma_f32 v77, v77, v101, v134
	v_mul_f32_e32 v133, v78, v110
	v_mul_f32_e32 v134, v70, v110
	v_fma_f32 v70, v70, v102, -v133
	v_fma_f32 v78, v78, v102, v134
	v_mul_f32_e32 v133, v79, v111
	v_mul_f32_e32 v134, v71, v111
	v_fma_f32 v71, v71, v103, -v133
	v_fma_f32 v79, v79, v103, v134
	v_mul_f32_e32 v133, v80, v112
	v_mul_f32_e32 v134, v72, v112
	v_fma_f32 v72, v72, v104, -v133
	v_fma_f32 v80, v80, v104, v134
	v_mul_f32_e32 v133, v81, v113
	v_mul_f32_e32 v134, v73, v113
	v_fma_f32 v73, v73, v105, -v133
	v_fma_f32 v81, v81, v105, v134
	v_cvt_pk_bf16_f32 v146, v50, v51
	v_cvt_pk_bf16_f32 v147, v52, v53
	v_cvt_pk_bf16_f32 v148, v54, v55
	v_cvt_pk_bf16_f32 v149, v56, v57
	v_cvt_pk_bf16_f32 v150, v58, v59
	v_cvt_pk_bf16_f32 v151, v60, v61
	v_cvt_pk_bf16_f32 v152, v62, v63
	v_cvt_pk_bf16_f32 v153, v64, v65
	v_cvt_pk_bf16_f32 v154, v66, v67
	v_cvt_pk_bf16_f32 v155, v68, v69
	v_cvt_pk_bf16_f32 v156, v70, v71
	v_cvt_pk_bf16_f32 v157, v72, v73
	v_cvt_pk_bf16_f32 v158, v74, v75
	v_cvt_pk_bf16_f32 v159, v76, v77
	v_cvt_pk_bf16_f32 v160, v78, v79
	v_cvt_pk_bf16_f32 v161, v80, v81
	v_lshlrev_b32_e32 v50, 16, v162
	v_and_b32_e32 v51, 0xffff0000, v162
	v_lshlrev_b32_e32 v52, 16, v163
	v_and_b32_e32 v53, 0xffff0000, v163
	v_lshlrev_b32_e32 v54, 16, v164
	v_and_b32_e32 v55, 0xffff0000, v164
	v_lshlrev_b32_e32 v56, 16, v165
	v_and_b32_e32 v57, 0xffff0000, v165
	v_lshlrev_b32_e32 v58, 16, v166
	v_and_b32_e32 v59, 0xffff0000, v166
	v_lshlrev_b32_e32 v60, 16, v167
	v_and_b32_e32 v61, 0xffff0000, v167
	v_lshlrev_b32_e32 v62, 16, v168
	v_and_b32_e32 v63, 0xffff0000, v168
	v_lshlrev_b32_e32 v64, 16, v169
	v_and_b32_e32 v65, 0xffff0000, v169
	v_lshlrev_b32_e32 v66, 16, v170
	v_and_b32_e32 v67, 0xffff0000, v170
	v_lshlrev_b32_e32 v68, 16, v171
	v_and_b32_e32 v69, 0xffff0000, v171
	v_lshlrev_b32_e32 v70, 16, v172
	v_and_b32_e32 v71, 0xffff0000, v172
	v_lshlrev_b32_e32 v72, 16, v173
	v_and_b32_e32 v73, 0xffff0000, v173
	v_lshlrev_b32_e32 v74, 16, v174
	v_and_b32_e32 v75, 0xffff0000, v174
	v_lshlrev_b32_e32 v76, 16, v175
	v_and_b32_e32 v77, 0xffff0000, v175
	v_lshlrev_b32_e32 v78, 16, v176
	v_and_b32_e32 v79, 0xffff0000, v176
	v_lshlrev_b32_e32 v80, 16, v177
	v_and_b32_e32 v81, 0xffff0000, v177
	v_mul_f32_e32 v130, v50, v50
	v_fmac_f32_e32 v130, v51, v51
	v_fmac_f32_e32 v130, v52, v52
	v_fmac_f32_e32 v130, v53, v53
	v_fmac_f32_e32 v130, v54, v54
	v_fmac_f32_e32 v130, v55, v55
	v_fmac_f32_e32 v130, v56, v56
	v_fmac_f32_e32 v130, v57, v57
	v_fmac_f32_e32 v130, v58, v58
	v_fmac_f32_e32 v130, v59, v59
	v_fmac_f32_e32 v130, v60, v60
	v_fmac_f32_e32 v130, v61, v61
	v_fmac_f32_e32 v130, v62, v62
	v_fmac_f32_e32 v130, v63, v63
	v_fmac_f32_e32 v130, v64, v64
	v_fmac_f32_e32 v130, v65, v65
	v_fmac_f32_e32 v130, v66, v66
	v_fmac_f32_e32 v130, v67, v67
	v_fmac_f32_e32 v130, v68, v68
	v_fmac_f32_e32 v130, v69, v69
	v_fmac_f32_e32 v130, v70, v70
	v_fmac_f32_e32 v130, v71, v71
	v_fmac_f32_e32 v130, v72, v72
	v_fmac_f32_e32 v130, v73, v73
	v_fmac_f32_e32 v130, v74, v74
	v_fmac_f32_e32 v130, v75, v75
	v_fmac_f32_e32 v130, v76, v76
	v_fmac_f32_e32 v130, v77, v77
	v_fmac_f32_e32 v130, v78, v78
	v_fmac_f32_e32 v130, v79, v79
	v_fmac_f32_e32 v130, v80, v80
	v_fmac_f32_e32 v130, v81, v81
	ds_swizzle_b32 v132, v130 offset:swizzle(SWAP,16)
	s_waitcnt lgkmcnt(0)
	v_add_f32_e32 v130, v130, v132
	v_mov_b32_e32 v132, v130
	s_nop 1
	v_permlane32_swap_b32_e32 v130, v132
	v_add_f32_e32 v130, v130, v132
	v_fmamk_f32 v130, v130, 0x3c000000, v199
	v_rsq_f32_e32 v130, v130
	s_nop 0
	v_mul_f32_e32 v131, s77, v130
	v_mul_f32_e32 v50, v50, v131
	v_mul_f32_e32 v50, v50, v18
	v_mul_f32_e32 v51, v51, v131
	v_mul_f32_e32 v51, v51, v19
	v_mul_f32_e32 v52, v52, v131
	v_mul_f32_e32 v52, v52, v20
	v_mul_f32_e32 v53, v53, v131
	v_mul_f32_e32 v53, v53, v21
	v_mul_f32_e32 v54, v54, v131
	v_mul_f32_e32 v54, v54, v22
	v_mul_f32_e32 v55, v55, v131
	v_mul_f32_e32 v55, v55, v23
	v_mul_f32_e32 v56, v56, v131
	v_mul_f32_e32 v56, v56, v24
	v_mul_f32_e32 v57, v57, v131
	v_mul_f32_e32 v57, v57, v25
	v_mul_f32_e32 v58, v58, v131
	v_mul_f32_e32 v58, v58, v26
	v_mul_f32_e32 v59, v59, v131
	v_mul_f32_e32 v59, v59, v27
	v_mul_f32_e32 v60, v60, v131
	v_mul_f32_e32 v60, v60, v28
	v_mul_f32_e32 v61, v61, v131
	v_mul_f32_e32 v61, v61, v29
	v_mul_f32_e32 v62, v62, v131
	v_mul_f32_e32 v62, v62, v30
	v_mul_f32_e32 v63, v63, v131
	v_mul_f32_e32 v63, v63, v31
	v_mul_f32_e32 v64, v64, v131
	v_mul_f32_e32 v64, v64, v32
	v_mul_f32_e32 v65, v65, v131
	v_mul_f32_e32 v65, v65, v33
	v_mul_f32_e32 v66, v66, v131
	v_mul_f32_e32 v66, v66, v34
	v_mul_f32_e32 v67, v67, v131
	v_mul_f32_e32 v67, v67, v35
	v_mul_f32_e32 v68, v68, v131
	v_mul_f32_e32 v68, v68, v36
	v_mul_f32_e32 v69, v69, v131
	v_mul_f32_e32 v69, v69, v37
	v_mul_f32_e32 v70, v70, v131
	v_mul_f32_e32 v70, v70, v38
	v_mul_f32_e32 v71, v71, v131
	v_mul_f32_e32 v71, v71, v39
	v_mul_f32_e32 v72, v72, v131
	v_mul_f32_e32 v72, v72, v40
	v_mul_f32_e32 v73, v73, v131
	v_mul_f32_e32 v73, v73, v41
	v_mul_f32_e32 v74, v74, v131
	v_mul_f32_e32 v74, v74, v42
	v_mul_f32_e32 v75, v75, v131
	v_mul_f32_e32 v75, v75, v43
	v_mul_f32_e32 v76, v76, v131
	v_mul_f32_e32 v76, v76, v44
	v_mul_f32_e32 v77, v77, v131
	v_mul_f32_e32 v77, v77, v45
	v_mul_f32_e32 v78, v78, v131
	v_mul_f32_e32 v78, v78, v46
	v_mul_f32_e32 v79, v79, v131
	v_mul_f32_e32 v79, v79, v47
	v_mul_f32_e32 v80, v80, v131
	v_mul_f32_e32 v80, v80, v48
	v_mul_f32_e32 v81, v81, v131
	v_mul_f32_e32 v81, v81, v49
	v_mul_f32_e32 v133, v58, v90
	v_mul_f32_e32 v134, v50, v90
	v_fma_f32 v50, v50, v82, -v133
	v_fma_f32 v58, v58, v82, v134
; #define SBAR() __builtin_amdgcn_sched_barrier(0)
; #define QF(d, e) __uint_as_float(((unsigned)(unsigned short)qr[d][e]) << 16)
; template <typename TQ> ...
;     ...
;         for (int e = 0; e < 8; e += 2) {
;           float o1[2], o2[2];
; #pragma unroll
;           for (int k = 0; k < 2; ++k) { const float x1 = QF(dl, e + k) * rn * gl[e + k], x2 = QF(du, e + k) * rn * gu[e + k]; const float c = cp[e + k], sn = sp[e + k];
;             o1[k] = x1 * c - x2 * sn; o2[k] = x2 * c + x1 * sn; }
;           wl[e >> 1] = cvtpk(o1[0], o1[1]); wu[e >> 1] = cvtpk(o2[0], o2[1]);
;         }
;         u32x4 vl = {wl[0], wl[1], wl[2], wl[3]}, vu = {wu[0], wu[1], wu[2], wu[3]};
;         qr[dl] = *reinterpret_cast<bf16x8*>(&vl); qr[du] = *reinterpret_cast<bf16x8*>(&vu);
;       }
;   }
;     ...
;   SBAR();
;   f32x16 pA0, pA1, pB0, pB1; bf16x8 pa0, pa1, pa2, pa3; const int NT = seq / KVBLK;
;   f32x16 negm;
; #pragma unroll
;   for (int r = 0; r < 16; ++r) negm[r] = -mC;
;   asm volatile("" : "+v"(negm));
;   asm volatile("s_waitcnt vmcnt(0)" ::: "memory"); SWRITE(0, SE); __syncthreads();
	v_mul_f32_e32 v133, v59, v91
	v_mul_f32_e32 v134, v51, v91
	v_fma_f32 v51, v51, v83, -v133
	v_fma_f32 v59, v59, v83, v134
	v_mul_f32_e32 v133, v60, v92
	v_mul_f32_e32 v134, v52, v92
	v_fma_f32 v52, v52, v84, -v133
	v_fma_f32 v60, v60, v84, v134
	v_mul_f32_e32 v133, v61, v93
	v_mul_f32_e32 v134, v53, v93
	v_fma_f32 v53, v53, v85, -v133
	v_fma_f32 v61, v61, v85, v134
	v_mul_f32_e32 v133, v62, v94
	v_mul_f32_e32 v134, v54, v94
	v_fma_f32 v54, v54, v86, -v133
	v_fma_f32 v62, v62, v86, v134
	v_mul_f32_e32 v133, v63, v95
	v_mul_f32_e32 v134, v55, v95
	v_fma_f32 v55, v55, v87, -v133
	v_fma_f32 v63, v63, v87, v134
	v_mul_f32_e32 v133, v64, v96
	v_mul_f32_e32 v134, v56, v96
	v_fma_f32 v56, v56, v88, -v133
	v_fma_f32 v64, v64, v88, v134
	v_mul_f32_e32 v133, v65, v97
	v_mul_f32_e32 v134, v57, v97
	v_fma_f32 v57, v57, v89, -v133
	v_fma_f32 v65, v65, v89, v134
	v_mul_f32_e32 v133, v74, v122
	v_mul_f32_e32 v134, v66, v122
	v_fma_f32 v66, v66, v114, -v133
	v_fma_f32 v74, v74, v114, v134
	v_mul_f32_e32 v133, v75, v123
	v_mul_f32_e32 v134, v67, v123
	v_fma_f32 v67, v67, v115, -v133
	v_fma_f32 v75, v75, v115, v134
	v_mul_f32_e32 v133, v76, v124
	v_mul_f32_e32 v134, v68, v124
	v_fma_f32 v68, v68, v116, -v133
	v_fma_f32 v76, v76, v116, v134
	v_mul_f32_e32 v133, v77, v125
	v_mul_f32_e32 v134, v69, v125
	v_fma_f32 v69, v69, v117, -v133
	v_fma_f32 v77, v77, v117, v134
	v_mul_f32_e32 v133, v78, v126
	v_mul_f32_e32 v134, v70, v126
	v_fma_f32 v70, v70, v118, -v133
	v_fma_f32 v78, v78, v118, v134
	v_mul_f32_e32 v133, v79, v127
	v_mul_f32_e32 v134, v71, v127
	v_fma_f32 v71, v71, v119, -v133
	v_fma_f32 v79, v79, v119, v134
	v_mul_f32_e32 v133, v80, v128
	v_mul_f32_e32 v134, v72, v128
	v_fma_f32 v72, v72, v120, -v133
	v_fma_f32 v80, v80, v120, v134
	v_mul_f32_e32 v133, v81, v129
	v_mul_f32_e32 v134, v73, v129
	v_fma_f32 v73, v73, v121, -v133
	v_fma_f32 v81, v81, v121, v134
	v_cvt_pk_bf16_f32 v162, v50, v51
	v_cvt_pk_bf16_f32 v163, v52, v53
	v_cvt_pk_bf16_f32 v164, v54, v55
	v_cvt_pk_bf16_f32 v165, v56, v57
	v_cvt_pk_bf16_f32 v166, v58, v59
	v_cvt_pk_bf16_f32 v167, v60, v61
	v_cvt_pk_bf16_f32 v168, v62, v63
	v_cvt_pk_bf16_f32 v169, v64, v65
	v_cvt_pk_bf16_f32 v170, v66, v67
	v_cvt_pk_bf16_f32 v171, v68, v69
	v_cvt_pk_bf16_f32 v172, v70, v71
	v_cvt_pk_bf16_f32 v173, v72, v73
	v_cvt_pk_bf16_f32 v174, v74, v75
	v_cvt_pk_bf16_f32 v175, v76, v77
	v_cvt_pk_bf16_f32 v176, v78, v79
	v_cvt_pk_bf16_f32 v177, v80, v81
	v_mov_b32_e32 v18, 0
	v_mov_b32_e32 v19, 0
	v_mov_b32_e32 v20, 0
	v_mov_b32_e32 v21, 0
	v_mov_b32_e32 v22, 0
	v_mov_b32_e32 v23, 0
	v_mov_b32_e32 v24, 0
	v_mov_b32_e32 v25, 0
	v_mov_b32_e32 v26, 0
	v_mov_b32_e32 v27, 0
	v_mov_b32_e32 v28, 0
	v_mov_b32_e32 v29, 0
	v_mov_b32_e32 v30, 0
	v_mov_b32_e32 v31, 0
	v_mov_b32_e32 v32, 0
	v_mov_b32_e32 v33, 0
	v_mov_b32_e32 v34, 0
	v_mov_b32_e32 v35, 0
	v_mov_b32_e32 v36, 0
	v_mov_b32_e32 v37, 0
	v_mov_b32_e32 v38, 0
	v_mov_b32_e32 v39, 0
	v_mov_b32_e32 v40, 0
	v_mov_b32_e32 v41, 0
	v_mov_b32_e32 v42, 0
	v_mov_b32_e32 v43, 0
	v_mov_b32_e32 v44, 0
	v_mov_b32_e32 v45, 0
	v_mov_b32_e32 v46, 0
	v_mov_b32_e32 v47, 0
	v_mov_b32_e32 v48, 0
	v_mov_b32_e32 v49, 0
	v_mov_b32_e32 v50, 0
	v_mov_b32_e32 v51, 0
	v_mov_b32_e32 v52, 0
	v_mov_b32_e32 v53, 0
	v_mov_b32_e32 v54, 0
	v_mov_b32_e32 v55, 0
	v_mov_b32_e32 v56, 0
	v_mov_b32_e32 v57, 0
	v_mov_b32_e32 v58, 0
	v_mov_b32_e32 v59, 0
	v_mov_b32_e32 v60, 0
	v_mov_b32_e32 v61, 0
	v_mov_b32_e32 v62, 0
	v_mov_b32_e32 v63, 0
	v_mov_b32_e32 v64, 0
	v_mov_b32_e32 v65, 0
	v_mov_b32_e32 v66, 0
	v_mov_b32_e32 v67, 0
	v_mov_b32_e32 v68, 0
	v_mov_b32_e32 v69, 0
	v_mov_b32_e32 v70, 0
	v_mov_b32_e32 v71, 0
	v_mov_b32_e32 v72, 0
	v_mov_b32_e32 v73, 0
	v_mov_b32_e32 v74, 0
	v_mov_b32_e32 v75, 0
	v_mov_b32_e32 v76, 0
	v_mov_b32_e32 v77, 0
	v_mov_b32_e32 v78, 0
	v_mov_b32_e32 v79, 0
	v_mov_b32_e32 v80, 0
	v_mov_b32_e32 v81, 0
	v_mov_b32_e32 v250, 0
	v_mov_b32_e32 v251, 0
	s_barrier
; __device__ __forceinline__ void partialSM(f32x16& p0, f32x16& p1, float mC) {
;   (void)mC; (void)p1;
;   for (int r = 0; r < 16; ++r) p0[r] = __builtin_amdgcn_exp2f(p0[r]);
; }
; __device__ __forceinline__ void qkt(f32x16& p0, f32x16& p1, const bf16* Ks, const bf16x8* qr, int r32, int hi, const f32x16& negm) {
; #pragma unroll
;   for (int d0 = 0; d0 < 8; ++d0) { int cb = (d0 * 16 + hi * 8) * 2;
;     bf16x8 b0 = *reinterpret_cast<const bf16x8*>((const char*)Ks + KSWZ(r32, cb));
;     bf16x8 b1 = *reinterpret_cast<const bf16x8*>((const char*)Ks + KSWZ(32 + r32, cb));
;     if (d0 == 0) { p0 = __builtin_amdgcn_mfma_f32_32x32x16_bf16(b0, qr[0], negm, 0, 0, 0); p1 = __builtin_amdgcn_mfma_f32_32x32x16_bf16(b1, qr[0], negm, 0, 0, 0); }
;     else { p0 = __builtin_amdgcn_mfma_f32_32x32x16_bf16(b0, qr[d0], p0, 0, 0, 0); p1 = __builtin_amdgcn_mfma_f32_32x32x16_bf16(b1, qr[d0], p1, 0, 0, 0); } }
; }
	ds_read_b128 v[178:181], v234 offset:0
	ds_read_b128 v[182:185], v234 offset:4096
	ds_read_b128 v[186:189], v234 offset:8192
	ds_read_b128 v[190:193], v234 offset:12288
	s_waitcnt lgkmcnt(3)
	v_mfma_f32_16x16x32_bf16 v[82:85], v[178:181], v[146:149], v[2:5]
	v_mfma_f32_16x16x32_bf16 v[86:89], v[178:181], v[162:165], v[2:5]
	ds_read_b128 v[178:181], v235 offset:0
	s_waitcnt lgkmcnt(3)
	v_mfma_f32_16x16x32_bf16 v[90:93], v[182:185], v[146:149], v[2:5]
	v_mfma_f32_16x16x32_bf16 v[94:97], v[182:185], v[162:165], v[2:5]
	ds_read_b128 v[182:185], v235 offset:4096
	s_waitcnt lgkmcnt(3)
	v_mfma_f32_16x16x32_bf16 v[98:101], v[186:189], v[146:149], v[2:5]
	v_mfma_f32_16x16x32_bf16 v[102:105], v[186:189], v[162:165], v[2:5]
	ds_read_b128 v[186:189], v235 offset:8192
	s_waitcnt lgkmcnt(3)
	v_mfma_f32_16x16x32_bf16 v[106:109], v[190:193], v[146:149], v[2:5]
	v_mfma_f32_16x16x32_bf16 v[110:113], v[190:193], v[162:165], v[2:5]
	ds_read_b128 v[190:193], v235 offset:12288
	s_waitcnt lgkmcnt(3)
	v_mfma_f32_16x16x32_bf16 v[82:85], v[178:181], v[150:153], v[82:85]
	v_mfma_f32_16x16x32_bf16 v[86:89], v[178:181], v[166:169], v[86:89]
	ds_read_b128 v[178:181], v236 offset:0
	s_waitcnt lgkmcnt(3)
	v_mfma_f32_16x16x32_bf16 v[90:93], v[182:185], v[150:153], v[90:93]
	v_mfma_f32_16x16x32_bf16 v[94:97], v[182:185], v[166:169], v[94:97]
	ds_read_b128 v[182:185], v236 offset:4096
	s_waitcnt lgkmcnt(3)
	v_mfma_f32_16x16x32_bf16 v[98:101], v[186:189], v[150:153], v[98:101]
	v_mfma_f32_16x16x32_bf16 v[102:105], v[186:189], v[166:169], v[102:105]
	ds_read_b128 v[186:189], v236 offset:8192
	s_waitcnt lgkmcnt(3)
	v_mfma_f32_16x16x32_bf16 v[106:109], v[190:193], v[150:153], v[106:109]
	v_mfma_f32_16x16x32_bf16 v[110:113], v[190:193], v[166:169], v[110:113]
	ds_read_b128 v[190:193], v236 offset:12288
	s_waitcnt lgkmcnt(3)
	v_mfma_f32_16x16x32_bf16 v[82:85], v[178:181], v[154:157], v[82:85]
	v_mfma_f32_16x16x32_bf16 v[86:89], v[178:181], v[170:173], v[86:89]
	ds_read_b128 v[178:181], v237 offset:0
	s_waitcnt lgkmcnt(3)
	v_mfma_f32_16x16x32_bf16 v[90:93], v[182:185], v[154:157], v[90:93]
	v_mfma_f32_16x16x32_bf16 v[94:97], v[182:185], v[170:173], v[94:97]
	ds_read_b128 v[182:185], v237 offset:4096
	s_waitcnt lgkmcnt(3)
	v_mfma_f32_16x16x32_bf16 v[98:101], v[186:189], v[154:157], v[98:101]
	v_mfma_f32_16x16x32_bf16 v[102:105], v[186:189], v[170:173], v[102:105]
	ds_read_b128 v[186:189], v237 offset:8192
	s_waitcnt lgkmcnt(3)
	v_mfma_f32_16x16x32_bf16 v[106:109], v[190:193], v[154:157], v[106:109]
	v_mfma_f32_16x16x32_bf16 v[110:113], v[190:193], v[170:173], v[110:113]
	ds_read_b128 v[190:193], v237 offset:12288
	s_waitcnt lgkmcnt(3)
	v_mfma_f32_16x16x32_bf16 v[82:85], v[178:181], v[158:161], v[82:85]
	v_mfma_f32_16x16x32_bf16 v[86:89], v[178:181], v[174:177], v[86:89]
	s_waitcnt lgkmcnt(2)
	v_mfma_f32_16x16x32_bf16 v[90:93], v[182:185], v[158:161], v[90:93]
	v_mfma_f32_16x16x32_bf16 v[94:97], v[182:185], v[174:177], v[94:97]
	s_waitcnt lgkmcnt(1)
	v_mfma_f32_16x16x32_bf16 v[98:101], v[186:189], v[158:161], v[98:101]
	v_mfma_f32_16x16x32_bf16 v[102:105], v[186:189], v[174:177], v[102:105]
	s_waitcnt lgkmcnt(0)
	v_mfma_f32_16x16x32_bf16 v[106:109], v[190:193], v[158:161], v[106:109]
	v_mfma_f32_16x16x32_bf16 v[110:113], v[190:193], v[174:177], v[110:113]
	s_nop 7
	v_exp_f32_e32 v82, v82
	v_exp_f32_e32 v83, v83
	v_exp_f32_e32 v84, v84
	v_exp_f32_e32 v85, v85
	v_exp_f32_e32 v86, v86
	v_exp_f32_e32 v87, v87
	v_exp_f32_e32 v88, v88
	v_exp_f32_e32 v89, v89
	v_exp_f32_e32 v90, v90
	v_exp_f32_e32 v91, v91
	v_exp_f32_e32 v92, v92
	v_exp_f32_e32 v93, v93
	v_exp_f32_e32 v94, v94
	v_exp_f32_e32 v95, v95
	v_exp_f32_e32 v96, v96
	v_exp_f32_e32 v97, v97
	v_exp_f32_e32 v98, v98
	v_exp_f32_e32 v99, v99
	v_exp_f32_e32 v100, v100
	v_exp_f32_e32 v101, v101
	v_exp_f32_e32 v102, v102
	v_exp_f32_e32 v103, v103
	v_exp_f32_e32 v104, v104
	v_exp_f32_e32 v105, v105
	v_exp_f32_e32 v106, v106
	v_exp_f32_e32 v107, v107
	v_exp_f32_e32 v108, v108
	v_exp_f32_e32 v109, v109
	v_exp_f32_e32 v110, v110
	v_exp_f32_e32 v111, v111
	v_exp_f32_e32 v112, v112
	v_exp_f32_e32 v113, v113
	ds_read_b128 v[178:181], v234 offset:16384
	ds_read_b128 v[182:185], v234 offset:20480
	ds_read_b128 v[186:189], v234 offset:24576
	ds_read_b128 v[190:193], v234 offset:28672
	s_cmp_lt_u32 s53, 256
	s_cbranch_scc1 .Lattn_noprio
	s_setprio 3
